# short-conv phase: the six conv-weight vector loads (same for every item of a thread) issued once per batch with the data loads instead of six serialized round trips per batch, on top of v43
# baseline (speedup 1.0000x reference)
; #define GAS __attribute__((address_space(1)))
; DI void phase_mix(const Ctx& C, bf16_t* Z, const float* lse_, int L, bool dry) {
;     ...
;     for (int base = gt; base < MTOK * 64; base += 4 * ngt) {
;         u32x4 xv[4][3], cv[4][3], bv[4];
; #pragma unroll
;         for (int k = 0; k < 4; ++k) {
;             const int idx = base + k * ngt; const int lrow = idx >> 6, c0 = (idx & 63) * 8, t = lrow & (SEQ - 1);
; #pragma unroll
;             for (int jj = 0; jj < 3; ++jj) {
;                 const int back = 2 - jj; xv[k][jj] = (u32x4){0u, 0u, 0u, 0u}; cv[k][jj] = (u32x4){0u, 0u, 0u, 0u};
;                 if (idx < MTOK * 64 && t >= back) { const bf16_t* zr = Z + (size_t)(lrow - back) * ZW + c0; xv[k][jj] = *(const GAS u32x4*)(zr + CX); cv[k][jj] = *(const GAS u32x4*)(zr + CC); }
;     ...
;                     const f32x4 w0 = *(const GAS f32x4*)(cw + jj * 512 + c0), w1 = *(const GAS f32x4*)(cw + jj * 512 + c0 + 4);
.LBB0_155:
	v_and_b32_e32 v114, 0x1f8, v121
	v_lshlrev_b32_e32 v176, 2, v114
	s_add_u32 s98, s12, 0x1000
	s_addc_u32 s99, s13, 0
	global_load_dwordx4 v[152:155], v176, s[12:13]
	global_load_dwordx4 v[156:159], v176, s[12:13] offset:16
	global_load_dwordx4 v[160:163], v176, s[12:13] offset:2048
	global_load_dwordx4 v[164:167], v176, s[12:13] offset:2064
	global_load_dwordx4 v[168:171], v176, s[98:99]
	global_load_dwordx4 v[172:175], v176, s[98:99] offset:16
	v_readlane_b32 s0, v253, 51
	v_ashrrev_i32_e32 v0, 6, v49
	v_lshlrev_b32_e32 v192, 1, v114
	v_readlane_b32 s1, v253, 52
	v_and_b32_e32 v1, 0xfff, v0
	v_cmp_lt_u32_e32 vcc, 1, v1
	v_lshl_add_u64 v[10:11], s[0:1], 0, v[192:193]
	v_mov_b32_e32 v84, 0
	v_mov_b32_e32 v104, 0
	v_mov_b32_e32 v105, 0
	v_mov_b32_e32 v106, 0
	v_mov_b32_e32 v107, 0
	v_mov_b32_e32 v108, 0
	v_mov_b32_e32 v109, 0
	v_mov_b32_e32 v110, 0
	v_mov_b32_e32 v111, 0
	s_and_saveexec_b64 s[0:1], vcc
	s_cbranch_execz .LBB0_157
	v_add_u32_e32 v2, -2, v0
	v_mad_i64_i32 v[2:3], s[2:3], v2, s51, v[10:11]
	v_add_co_u32_e32 v2, vcc, 0x1000, v2
	s_nop 1
	v_addc_co_u32_e32 v3, vcc, 0, v3, vcc
	global_load_dwordx4 v[104:107], v[2:3], off offset:512
	global_load_dwordx4 v[108:111], v[2:3], off offset:2560

; __device__ __forceinline__ unsigned cvt_pk_bf16(float lo, float hi) { unsigned r; asm volatile("v_cvt_pk_bf16_f32 %0, %1, %2" : "=v"(r) : "v"(lo), "v"(hi)); return r; }
; #define GAS __attribute__((address_space(1)))
; DI float bf_lo(unsigned w) { return __uint_as_float(w << 16); }
; DI float bf_hi(unsigned w) { return __uint_as_float(w & 0xffff0000u); }
; DI void phase_mix(const Ctx& C, bf16_t* Z, const float* lse_, int L, bool dry) {
;     ...
;         for (int k = 0; k < 4; ++k) {
;             const int idx = base + k * ngt; const int lrow = idx >> 6, c0 = (idx & 63) * 8;
;             if (idx < MTOK * 64) {
;                 float accv[8];
; #pragma unroll
;                 for (int e = 0; e < 8; ++e) accv[e] = 0.f;
; #pragma unroll
;                 for (int jj = 0; jj < 3; ++jj) {
;                     const f32x4 w0 = *(const GAS f32x4*)(cw + jj * 512 + c0), w1 = *(const GAS f32x4*)(cw + jj * 512 + c0 + 4);
;                     const u32x4 x_ = xv[k][jj], c_ = cv[k][jj];
;                     accv[0] += w0.x * bf_lo(x_.x) * bf_lo(c_.x); accv[1] += w0.y * bf_hi(x_.x) * bf_hi(c_.x);
;                     accv[2] += w0.z * bf_lo(x_.y) * bf_lo(c_.y); accv[3] += w0.w * bf_hi(x_.y) * bf_hi(c_.y);
;                     accv[4] += w1.x * bf_lo(x_.z) * bf_lo(c_.z); accv[5] += w1.y * bf_hi(x_.z) * bf_hi(c_.z);
;                     accv[6] += w1.z * bf_lo(x_.w) * bf_lo(c_.w); accv[7] += w1.w * bf_hi(x_.w) * bf_hi(c_.w);
;                 }
;                 bf16_t* bp = Z + (size_t)lrow * ZW + CB + c0;
;                 u32x4 w;
;                 w.x = cvt_pk_bf16(bf_lo(bv[k].x) * accv[0], bf_hi(bv[k].x) * accv[1]); w.y = cvt_pk_bf16(bf_lo(bv[k].y) * accv[2], bf_hi(bv[k].y) * accv[3]);
;                 w.z = cvt_pk_bf16(bf_lo(bv[k].z) * accv[4], bf_hi(bv[k].z) * accv[5]); w.w = cvt_pk_bf16(bf_lo(bv[k].w) * accv[6], bf_hi(bv[k].w) * accv[7]);
;                 *(GAS u32x4*)(dry ? dummy : bp) = w;
.LBB0_183:
	s_or_b64 exec, exec, s[6:7]
	v_lshlrev_b32_e32 v114, 2, v114
	s_waitcnt vmcnt(0)
	v_mov_b32_e32 v130, v156
	v_mov_b32_e32 v131, v157
	v_mov_b32_e32 v132, v158
	v_mov_b32_e32 v133, v159
	v_mov_b32_e32 v126, v152
	v_mov_b32_e32 v127, v153
	v_mov_b32_e32 v128, v154
	v_mov_b32_e32 v129, v155
	s_mov_b64 s[2:3], 0x1600
	v_mov_b32_e32 v115, v193
	v_lshl_add_u64 v[116:117], v[112:113], 0, s[2:3]
	v_lshl_add_u64 v[112:113], s[12:13], 0, v[114:115]
	v_lshlrev_b32_e32 v115, 16, v104
	v_and_b32_e32 v104, 0xffff0000, v104
	s_mov_b64 s[2:3], 0x1000
	v_lshlrev_b32_e32 v138, 16, v84
	v_lshlrev_b32_e32 v139, 16, v100
	v_mul_f32_e32 v115, v126, v115
	v_lshlrev_b32_e32 v126, 16, v108
	v_mul_f32_e32 v104, v127, v104
	v_and_b32_e32 v108, 0xffff0000, v108
	v_fma_f32 v144, v104, v108, 0
	v_lshlrev_b32_e32 v104, 16, v105
	v_mul_f32_e32 v104, v128, v104
	v_lshlrev_b32_e32 v108, 16, v109
	v_fma_f32 v145, v104, v108, 0
	v_and_b32_e32 v104, 0xffff0000, v105
	v_mul_f32_e32 v104, v129, v104
	v_and_b32_e32 v105, 0xffff0000, v109
	v_fma_f32 v146, v104, v105, 0
	v_lshlrev_b32_e32 v104, 16, v106
	v_mul_f32_e32 v104, v130, v104
	v_lshlrev_b32_e32 v105, 16, v110
	v_fma_f32 v129, v104, v105, 0
	v_and_b32_e32 v104, 0xffff0000, v106
	v_mul_f32_e32 v104, v131, v104
	v_and_b32_e32 v105, 0xffff0000, v110
	v_fma_f32 v128, v104, v105, 0
	v_lshlrev_b32_e32 v104, 16, v107
	v_mul_f32_e32 v104, v132, v104
	v_lshlrev_b32_e32 v105, 16, v111
	v_fma_f32 v127, v104, v105, 0
	v_and_b32_e32 v104, 0xffff0000, v107
	v_mul_f32_e32 v104, v133, v104
	v_and_b32_e32 v105, 0xffff0000, v111
	v_fma_f32 v141, v115, v126, 0
	v_fma_f32 v126, v104, v105, 0
	v_mov_b32_e32 v104, v164
	v_mov_b32_e32 v105, v165
	v_mov_b32_e32 v106, v166
	v_mov_b32_e32 v107, v167
	v_mov_b32_e32 v130, v160
	v_mov_b32_e32 v131, v161
	v_mov_b32_e32 v132, v162
	v_mov_b32_e32 v133, v163
	v_lshl_add_u64 v[114:115], v[112:113], 0, s[2:3]
	s_movk_i32 s2, 0x1000
	v_add_co_u32_e32 v108, vcc, s2, v112
	v_mov_b32_e32 v142, v130
	v_addc_co_u32_e32 v109, vcc, 0, v113, vcc
	v_mov_b32_e32 v134, v168
	v_mov_b32_e32 v135, v169
	v_mov_b32_e32 v136, v170
	v_mov_b32_e32 v137, v171
	s_nop 0
	v_mov_b32_e32 v108, v172
	v_mov_b32_e32 v109, v173
	v_mov_b32_e32 v110, v174
	v_mov_b32_e32 v111, v175
	v_mov_b32_e32 v143, v134
	v_pk_mul_f32 v[138:139], v[142:143], v[138:139]
	v_lshlrev_b32_e32 v142, 16, v88
	v_lshlrev_b32_e32 v143, 16, v96
	v_pk_mul_f32 v[138:139], v[138:139], v[142:143]
	v_mov_b32_e32 v134, v131
	v_add_f32_e32 v130, v141, v138
	v_add_f32_e32 v141, v130, v139
	v_and_b32_e32 v139, 0xffff0000, v100
	v_and_b32_e32 v138, 0xffff0000, v84
	v_pk_mul_f32 v[130:131], v[134:135], v[138:139]
	v_and_b32_e32 v135, 0xffff0000, v96
	v_and_b32_e32 v134, 0xffff0000, v88
	v_pk_mul_f32 v[130:131], v[130:131], v[134:135]
	v_mov_b32_e32 v134, v132
	v_add_f32_e32 v84, v144, v130
	v_add_f32_e32 v138, v84, v131
	v_lshlrev_b32_e32 v130, 16, v85
	v_lshlrev_b32_e32 v131, 16, v101
	v_mov_b32_e32 v135, v136
	v_pk_mul_f32 v[130:131], v[134:135], v[130:131]
	v_lshlrev_b32_e32 v134, 16, v89
	v_lshlrev_b32_e32 v135, 16, v97
	v_pk_mul_f32 v[130:131], v[130:131], v[134:135]
	v_and_b32_e32 v101, 0xffff0000, v101
	v_add_f32_e32 v84, v145, v130
	v_and_b32_e32 v100, 0xffff0000, v85
	v_mov_b32_e32 v136, v133
	v_add_f32_e32 v130, v84, v131
	v_pk_mul_f32 v[84:85], v[136:137], v[100:101]
	v_and_b32_e32 v97, 0xffff0000, v97
	v_and_b32_e32 v96, 0xffff0000, v89
	v_pk_mul_f32 v[84:85], v[84:85], v[96:97]
	v_mov_b32_e32 v88, v104
	v_add_f32_e32 v84, v146, v84
	v_add_f32_e32 v96, v84, v85
	v_lshlrev_b32_e32 v84, 16, v86
	v_lshlrev_b32_e32 v85, 16, v102
	v_mov_b32_e32 v89, v108
	v_pk_mul_f32 v[84:85], v[88:89], v[84:85]
	v_lshlrev_b32_e32 v88, 16, v90
	v_lshlrev_b32_e32 v89, 16, v98
	v_pk_mul_f32 v[84:85], v[84:85], v[88:89]
	v_mov_b32_e32 v108, v105
	v_add_f32_e32 v84, v129, v84
	v_add_f32_e32 v97, v84, v85
	v_and_b32_e32 v85, 0xffff0000, v102
	v_and_b32_e32 v84, 0xffff0000, v86
	v_pk_mul_f32 v[84:85], v[108:109], v[84:85]
	v_and_b32_e32 v89, 0xffff0000, v98
	v_and_b32_e32 v88, 0xffff0000, v90
	v_pk_mul_f32 v[84:85], v[84:85], v[88:89]
	v_mov_b32_e32 v88, v106
	v_add_f32_e32 v84, v128, v84
	v_add_f32_e32 v90, v84, v85
	v_lshlrev_b32_e32 v84, 16, v87
	v_lshlrev_b32_e32 v85, 16, v103
	v_mov_b32_e32 v89, v110
	v_pk_mul_f32 v[84:85], v[88:89], v[84:85]
	v_lshlrev_b32_e32 v88, 16, v91
	v_lshlrev_b32_e32 v89, 16, v99
	v_pk_mul_f32 v[84:85], v[84:85], v[88:89]
	v_mov_b32_e32 v110, v107
	v_add_f32_e32 v84, v127, v84
	v_add_f32_e32 v88, v84, v85
	v_and_b32_e32 v85, 0xffff0000, v103
	v_and_b32_e32 v84, 0xffff0000, v87
	v_pk_mul_f32 v[84:85], v[110:111], v[84:85]
	v_and_b32_e32 v87, 0xffff0000, v99
	v_and_b32_e32 v86, 0xffff0000, v91
	v_pk_mul_f32 v[84:85], v[84:85], v[86:87]
	v_and_b32_e32 v86, 0xffff0000, v93
	v_add_f32_e32 v84, v126, v84
	v_add_f32_e32 v87, v84, v85
	v_lshlrev_b32_e32 v84, 16, v92
	v_and_b32_e32 v85, 0xffff0000, v92
	v_mul_f32_e32 v84, v141, v84
	v_mul_f32_e32 v85, v138, v85
	v_cvt_pk_bf16_f32 v84, v84, v85
	v_lshlrev_b32_e32 v85, 16, v93
	v_mul_f32_e32 v85, v130, v85
	v_mul_f32_e32 v86, v96, v86
	v_cvt_pk_bf16_f32 v85, v85, v86
	v_lshlrev_b32_e32 v86, 16, v94
	v_and_b32_e32 v89, 0xffff0000, v94
	v_mul_f32_e32 v86, v97, v86
	v_mul_f32_e32 v89, v90, v89
	v_cvt_pk_bf16_f32 v86, v86, v89
	v_lshlrev_b32_e32 v89, 16, v95
	v_mul_f32_e32 v88, v88, v89
	v_and_b32_e32 v89, 0xffff0000, v95
	v_mul_f32_e32 v87, v87, v89
	v_cvt_pk_bf16_f32 v87, v88, v87
	global_store_dwordx4 v[116:117], v[84:87], off
	s_and_saveexec_b64 s[6:7], s[4:5]
	s_cbranch_execz .LBB0_186
; __device__ __forceinline__ unsigned cvt_pk_bf16(float lo, float hi) { unsigned r; asm volatile("v_cvt_pk_bf16_f32 %0, %1, %2" : "=v"(r) : "v"(lo), "v"(hi)); return r; }
; #define GAS __attribute__((address_space(1)))
; DI float bf_lo(unsigned w) { return __uint_as_float(w << 16); }
; DI float bf_hi(unsigned w) { return __uint_as_float(w & 0xffff0000u); }
; DI void phase_mix(const Ctx& C, bf16_t* Z, const float* lse_, int L, bool dry) {
;     ...
;         for (int k = 0; k < 4; ++k) {
;             const int idx = base + k * ngt; const int lrow = idx >> 6, c0 = (idx & 63) * 8;
;             if (idx < MTOK * 64) {
;                 float accv[8];
; #pragma unroll
;                 for (int e = 0; e < 8; ++e) accv[e] = 0.f;
; #pragma unroll
;                 for (int jj = 0; jj < 3; ++jj) {
;                     const f32x4 w0 = *(const GAS f32x4*)(cw + jj * 512 + c0), w1 = *(const GAS f32x4*)(cw + jj * 512 + c0 + 4);
;                     const u32x4 x_ = xv[k][jj], c_ = cv[k][jj];
;                     accv[0] += w0.x * bf_lo(x_.x) * bf_lo(c_.x); accv[1] += w0.y * bf_hi(x_.x) * bf_hi(c_.x);
;                     accv[2] += w0.z * bf_lo(x_.y) * bf_lo(c_.y); accv[3] += w0.w * bf_hi(x_.y) * bf_hi(c_.y);
;                     accv[4] += w1.x * bf_lo(x_.z) * bf_lo(c_.z); accv[5] += w1.y * bf_hi(x_.z) * bf_hi(c_.z);
;                     accv[6] += w1.z * bf_lo(x_.w) * bf_lo(c_.w); accv[7] += w1.w * bf_hi(x_.w) * bf_hi(c_.w);
;                 }
;                 bf16_t* bp = Z + (size_t)lrow * ZW + CB + c0;
;                 u32x4 w;
;                 w.x = cvt_pk_bf16(bf_lo(bv[k].x) * accv[0], bf_hi(bv[k].x) * accv[1]); w.y = cvt_pk_bf16(bf_lo(bv[k].y) * accv[2], bf_hi(bv[k].y) * accv[3]);
;                 w.z = cvt_pk_bf16(bf_lo(bv[k].z) * accv[4], bf_hi(bv[k].z) * accv[5]); w.w = cvt_pk_bf16(bf_lo(bv[k].w) * accv[6], bf_hi(bv[k].w) * accv[7]);
;                 *(GAS u32x4*)(dry ? dummy : bp) = w;
	v_mov_b32_e32 v96, v152
	v_mov_b32_e32 v97, v153
	v_mov_b32_e32 v98, v154
	v_mov_b32_e32 v99, v155
	v_mov_b32_e32 v92, v156
	v_mov_b32_e32 v93, v157
	v_mov_b32_e32 v94, v158
	v_mov_b32_e32 v95, v159
	v_mov_b32_e32 v100, v160
	v_mov_b32_e32 v101, v161
	v_mov_b32_e32 v102, v162
	v_mov_b32_e32 v103, v163
	v_mov_b32_e32 v104, v168
	v_mov_b32_e32 v105, v169
	v_mov_b32_e32 v106, v170
	v_mov_b32_e32 v107, v171
	v_mov_b32_e32 v88, v164
	v_mov_b32_e32 v89, v165
	v_mov_b32_e32 v90, v166
	v_mov_b32_e32 v91, v167
	v_mov_b32_e32 v84, v172
	v_mov_b32_e32 v85, v173
	v_mov_b32_e32 v86, v174
	v_mov_b32_e32 v87, v175
	v_and_b32_e32 v130, 0xffff0000, v77
	v_and_b32_e32 v134, 0xffff0000, v78
	v_and_b32_e32 v138, 0xffff0000, v79
	v_lshlrev_b32_e32 v116, 16, v76
	v_and_b32_e32 v126, 0xffff0000, v76
	v_lshlrev_b32_e32 v128, 16, v77
	v_lshlrev_b32_e32 v129, 16, v81
	v_and_b32_e32 v131, 0xffff0000, v81
	v_lshlrev_b32_e32 v132, 16, v78
	v_lshlrev_b32_e32 v77, 16, v72
	v_and_b32_e32 v81, 0xffff0000, v72
	v_lshlrev_b32_e32 v109, 16, v73
	v_and_b32_e32 v73, 0xffff0000, v73
	v_and_b32_e32 v72, 0xffff0000, v57
	v_lshlrev_b32_e32 v117, 16, v80
	v_and_b32_e32 v127, 0xffff0000, v80
	v_lshlrev_b32_e32 v133, 16, v82
	v_and_b32_e32 v135, 0xffff0000, v82
	v_lshlrev_b32_e32 v76, 16, v56
	v_lshlrev_b32_e32 v78, 16, v60
	v_and_b32_e32 v80, 0xffff0000, v56
	v_and_b32_e32 v82, 0xffff0000, v60
	v_lshlrev_b32_e32 v108, 16, v57
	v_lshlrev_b32_e32 v110, 16, v61
	v_and_b32_e32 v57, 0xffff0000, v69
	v_and_b32_e32 v56, 0xffff0000, v61
	v_lshlrev_b32_e32 v61, 16, v74
	v_lshlrev_b32_e32 v60, 16, v58
	v_lshlrev_b32_e32 v136, 16, v79
	v_lshlrev_b32_e32 v137, 16, v83
	v_and_b32_e32 v139, 0xffff0000, v83
	v_lshlrev_b32_e32 v79, 16, v68
	v_and_b32_e32 v83, 0xffff0000, v68
	v_lshlrev_b32_e32 v111, 16, v69
	v_lshlrev_b32_e32 v69, 16, v70
	v_lshlrev_b32_e32 v68, 16, v62
	v_readlane_b32 s2, v253, 51
	v_readlane_b32 s3, v253, 52
	v_mul_f32_e32 v99, v99, v130
	v_mul_f32_e32 v130, v93, v134
	v_mul_f32_e32 v134, v95, v138
	v_mov_b32_e32 v95, v106
	v_mov_b32_e32 v106, v103
	v_mul_f32_e32 v116, v96, v116
	v_mul_f32_e32 v126, v97, v126
	v_mul_f32_e32 v98, v98, v128
	v_mul_f32_e32 v128, v92, v132
	v_mov_b32_e32 v92, v100
	v_mov_b32_e32 v93, v104
	v_mov_b32_e32 v96, v88
	v_mov_b32_e32 v97, v84
	v_pk_mul_f32 v[72:73], v[106:107], v[72:73]
	v_fma_f32 v99, v99, v131, 0
	v_pk_mul_f32 v[76:77], v[92:93], v[76:77]
	v_pk_mul_f32 v[60:61], v[96:97], v[60:61]
	v_pk_mul_f32 v[56:57], v[72:73], v[56:57]
	v_fma_f32 v84, v116, v117, 0
	v_fma_f32 v100, v128, v133, 0
	v_pk_mul_f32 v[76:77], v[76:77], v[78:79]
	v_pk_mul_f32 v[60:61], v[60:61], v[68:69]
	v_add_f32_e32 v56, v99, v56
	v_add_f32_e32 v68, v84, v76
	v_add_f32_e32 v60, v100, v60
	v_add_f32_e32 v73, v56, v57
	v_and_b32_e32 v57, 0xffff0000, v74
	v_and_b32_e32 v56, 0xffff0000, v58
	v_mov_b32_e32 v84, v89
	v_add_f32_e32 v76, v60, v61
	v_pk_mul_f32 v[56:57], v[84:85], v[56:57]
	v_and_b32_e32 v61, 0xffff0000, v70
	v_and_b32_e32 v60, 0xffff0000, v62
	v_mov_b32_e32 v104, v101
	v_fma_f32 v101, v130, v135, 0
	v_pk_mul_f32 v[56:57], v[56:57], v[60:61]
	v_mov_b32_e32 v60, v90
	v_add_f32_e32 v56, v101, v56
	v_add_f32_e32 v62, v56, v57
	v_lshlrev_b32_e32 v56, 16, v59
	v_lshlrev_b32_e32 v57, 16, v75
	v_mov_b32_e32 v61, v86
	v_mul_f32_e32 v132, v94, v136
	v_pk_mul_f32 v[56:57], v[60:61], v[56:57]
	v_lshlrev_b32_e32 v60, 16, v63
	v_lshlrev_b32_e32 v61, 16, v71
	v_mov_b32_e32 v94, v102
	v_fma_f32 v102, v132, v137, 0
	v_pk_mul_f32 v[56:57], v[56:57], v[60:61]
	v_mov_b32_e32 v86, v91
	v_add_f32_e32 v56, v102, v56
	v_add_f32_e32 v70, v56, v57
	v_and_b32_e32 v57, 0xffff0000, v75
	v_and_b32_e32 v56, 0xffff0000, v59
	v_pk_mul_f32 v[56:57], v[86:87], v[56:57]
	v_and_b32_e32 v59, 0xffff0000, v71
	v_and_b32_e32 v58, 0xffff0000, v63
	v_fma_f32 v103, v134, v139, 0
	v_pk_mul_f32 v[56:57], v[56:57], v[58:59]
	v_pk_mul_f32 v[80:81], v[104:105], v[80:81]
	v_add_f32_e32 v56, v103, v56
	v_fma_f32 v88, v126, v127, 0
	v_pk_mul_f32 v[78:79], v[80:81], v[82:83]
	v_add_f32_e32 v59, v56, v57
	v_mov_b64_e32 v[56:57], s[2:3]
	v_pk_mul_f32 v[92:93], v[94:95], v[108:109]
	v_add_f32_e32 v69, v88, v78
	v_mad_i64_i32 v[56:57], s[2:3], v125, s51, v[56:57]
	v_fma_f32 v98, v98, v129, 0
	v_pk_mul_f32 v[80:81], v[92:93], v[110:111]
	v_add_f32_e32 v68, v68, v77
	v_add_f32_e32 v69, v69, v79
	v_lshl_add_u64 v[60:61], v[56:57], 0, v[192:193]
	v_lshlrev_b32_e32 v56, 16, v64
	v_and_b32_e32 v57, 0xffff0000, v64
	v_add_f32_e32 v72, v98, v80
	v_mul_f32_e32 v56, v68, v56
	v_mul_f32_e32 v57, v69, v57
	v_add_f32_e32 v72, v72, v81
	v_cvt_pk_bf16_f32 v56, v56, v57
	v_lshlrev_b32_e32 v57, 16, v65
	v_and_b32_e32 v58, 0xffff0000, v65
	v_mul_f32_e32 v57, v72, v57
	v_mul_f32_e32 v58, v73, v58
	v_cvt_pk_bf16_f32 v57, v57, v58
	v_lshlrev_b32_e32 v58, 16, v66
	v_and_b32_e32 v63, 0xffff0000, v66
	v_mul_f32_e32 v58, v76, v58
	v_mul_f32_e32 v62, v62, v63
	v_and_b32_e32 v63, 0xffff0000, v67
	v_add_co_u32_e32 v60, vcc, 0x1000, v60
	v_cvt_pk_bf16_f32 v58, v58, v62
	v_lshlrev_b32_e32 v62, 16, v67
	v_mul_f32_e32 v59, v59, v63
	v_addc_co_u32_e32 v61, vcc, 0, v61, vcc
	v_mul_f32_e32 v62, v70, v62
	v_cvt_pk_bf16_f32 v59, v62, v59
	global_store_dwordx4 v[60:61], v[56:59], off offset:1536
	s_or_b64 exec, exec, s[6:7]
	s_and_saveexec_b64 s[4:5], s[8:9]
	s_cbranch_execnz .LBB0_187

; __device__ __forceinline__ unsigned cvt_pk_bf16(float lo, float hi) { unsigned r; asm volatile("v_cvt_pk_bf16_f32 %0, %1, %2" : "=v"(r) : "v"(lo), "v"(hi)); return r; }
; #define GAS __attribute__((address_space(1)))
; DI float bf_lo(unsigned w) { return __uint_as_float(w << 16); }
; DI float bf_hi(unsigned w) { return __uint_as_float(w & 0xffff0000u); }
; DI void phase_mix(const Ctx& C, bf16_t* Z, const float* lse_, int L, bool dry) {
;     ...
;         for (int k = 0; k < 4; ++k) {
;             const int idx = base + k * ngt; const int lrow = idx >> 6, c0 = (idx & 63) * 8;
;             if (idx < MTOK * 64) {
;                 float accv[8];
; #pragma unroll
;                 for (int e = 0; e < 8; ++e) accv[e] = 0.f;
; #pragma unroll
;                 for (int jj = 0; jj < 3; ++jj) {
;                     const f32x4 w0 = *(const GAS f32x4*)(cw + jj * 512 + c0), w1 = *(const GAS f32x4*)(cw + jj * 512 + c0 + 4);
;                     const u32x4 x_ = xv[k][jj], c_ = cv[k][jj];
;                     accv[0] += w0.x * bf_lo(x_.x) * bf_lo(c_.x); accv[1] += w0.y * bf_hi(x_.x) * bf_hi(c_.x);
;                     accv[2] += w0.z * bf_lo(x_.y) * bf_lo(c_.y); accv[3] += w0.w * bf_hi(x_.y) * bf_hi(c_.y);
;                     accv[4] += w1.x * bf_lo(x_.z) * bf_lo(c_.z); accv[5] += w1.y * bf_hi(x_.z) * bf_hi(c_.z);
;                     accv[6] += w1.z * bf_lo(x_.w) * bf_lo(c_.w); accv[7] += w1.w * bf_hi(x_.w) * bf_hi(c_.w);
;                 }
;                 bf16_t* bp = Z + (size_t)lrow * ZW + CB + c0;
;                 u32x4 w;
;                 w.x = cvt_pk_bf16(bf_lo(bv[k].x) * accv[0], bf_hi(bv[k].x) * accv[1]); w.y = cvt_pk_bf16(bf_lo(bv[k].y) * accv[2], bf_hi(bv[k].y) * accv[3]);
;                 w.z = cvt_pk_bf16(bf_lo(bv[k].z) * accv[4], bf_hi(bv[k].z) * accv[5]); w.w = cvt_pk_bf16(bf_lo(bv[k].w) * accv[6], bf_hi(bv[k].w) * accv[7]);
;                 *(GAS u32x4*)(dry ? dummy : bp) = w;
.LBB0_187:
	v_mov_b32_e32 v68, v152
	v_mov_b32_e32 v69, v153
	v_mov_b32_e32 v70, v154
	v_mov_b32_e32 v71, v155
	v_mov_b32_e32 v64, v156
	v_mov_b32_e32 v65, v157
	v_mov_b32_e32 v66, v158
	v_mov_b32_e32 v67, v159
	v_mov_b32_e32 v72, v160
	v_mov_b32_e32 v73, v161
	v_mov_b32_e32 v74, v162
	v_mov_b32_e32 v75, v163
	v_mov_b32_e32 v76, v168
	v_mov_b32_e32 v77, v169
	v_mov_b32_e32 v78, v170
	v_mov_b32_e32 v79, v171
	v_mov_b32_e32 v60, v164
	v_mov_b32_e32 v61, v165
	v_mov_b32_e32 v62, v166
	v_mov_b32_e32 v63, v167
	v_mov_b32_e32 v56, v172
	v_mov_b32_e32 v57, v173
	v_mov_b32_e32 v58, v174
	v_mov_b32_e32 v59, v175
	v_and_b32_e32 v90, 0xffff0000, v49
	v_and_b32_e32 v94, 0xffff0000, v50
	v_and_b32_e32 v98, 0xffff0000, v51
	v_lshlrev_b32_e32 v84, 16, v48
	v_and_b32_e32 v86, 0xffff0000, v48
	v_lshlrev_b32_e32 v88, 16, v49
	v_lshlrev_b32_e32 v89, 16, v53
	v_and_b32_e32 v91, 0xffff0000, v53
	v_lshlrev_b32_e32 v92, 16, v50
	v_lshlrev_b32_e32 v49, 16, v44
	v_and_b32_e32 v53, 0xffff0000, v44
	v_lshlrev_b32_e32 v81, 16, v45
	v_and_b32_e32 v45, 0xffff0000, v45
	v_and_b32_e32 v44, 0xffff0000, v29
	v_lshlrev_b32_e32 v85, 16, v52
	v_and_b32_e32 v87, 0xffff0000, v52
	v_lshlrev_b32_e32 v93, 16, v54
	v_and_b32_e32 v95, 0xffff0000, v54
	v_lshlrev_b32_e32 v48, 16, v28
	v_lshlrev_b32_e32 v50, 16, v32
	v_and_b32_e32 v52, 0xffff0000, v28
	v_and_b32_e32 v54, 0xffff0000, v32
	v_lshlrev_b32_e32 v80, 16, v29
	v_lshlrev_b32_e32 v82, 16, v33
	v_and_b32_e32 v29, 0xffff0000, v41
	v_and_b32_e32 v28, 0xffff0000, v33
	v_lshlrev_b32_e32 v33, 16, v46
	v_lshlrev_b32_e32 v32, 16, v30
	v_lshlrev_b32_e32 v96, 16, v51
	v_lshlrev_b32_e32 v97, 16, v55
	v_and_b32_e32 v99, 0xffff0000, v55
	v_lshlrev_b32_e32 v51, 16, v40
	v_and_b32_e32 v55, 0xffff0000, v40
	v_lshlrev_b32_e32 v83, 16, v41
	v_lshlrev_b32_e32 v41, 16, v42
	v_lshlrev_b32_e32 v40, 16, v34
	v_readlane_b32 s2, v253, 51
	v_readlane_b32 s3, v253, 52
	v_mul_f32_e32 v71, v71, v90
	v_mul_f32_e32 v90, v65, v94
	v_mul_f32_e32 v94, v67, v98
	v_mov_b32_e32 v67, v78
	v_mov_b32_e32 v78, v75
	v_mul_f32_e32 v84, v68, v84
	v_mul_f32_e32 v86, v69, v86
	v_mul_f32_e32 v70, v70, v88
	v_mul_f32_e32 v88, v64, v92
	v_mov_b32_e32 v64, v72
	v_mov_b32_e32 v65, v76
	v_mov_b32_e32 v68, v60
	v_mov_b32_e32 v69, v56
	v_pk_mul_f32 v[44:45], v[78:79], v[44:45]
	v_fma_f32 v71, v71, v91, 0
	v_pk_mul_f32 v[48:49], v[64:65], v[48:49]
	v_pk_mul_f32 v[32:33], v[68:69], v[32:33]
	v_pk_mul_f32 v[28:29], v[44:45], v[28:29]
	v_fma_f32 v56, v84, v85, 0
	v_fma_f32 v72, v88, v93, 0
	v_pk_mul_f32 v[48:49], v[48:49], v[50:51]
	v_pk_mul_f32 v[32:33], v[32:33], v[40:41]
	v_add_f32_e32 v28, v71, v28
	v_add_f32_e32 v40, v56, v48
	v_add_f32_e32 v32, v72, v32
	v_add_f32_e32 v45, v28, v29
	v_and_b32_e32 v29, 0xffff0000, v46
	v_and_b32_e32 v28, 0xffff0000, v30
	v_mov_b32_e32 v56, v61
	v_add_f32_e32 v48, v32, v33
	v_pk_mul_f32 v[28:29], v[56:57], v[28:29]
	v_and_b32_e32 v33, 0xffff0000, v42
	v_and_b32_e32 v32, 0xffff0000, v34
	v_mov_b32_e32 v76, v73
	v_fma_f32 v73, v90, v95, 0
	v_pk_mul_f32 v[28:29], v[28:29], v[32:33]
	v_mov_b32_e32 v32, v62
	v_add_f32_e32 v28, v73, v28
	v_add_f32_e32 v34, v28, v29
	v_lshlrev_b32_e32 v28, 16, v31
	v_lshlrev_b32_e32 v29, 16, v47
	v_mov_b32_e32 v33, v58
	v_mul_f32_e32 v92, v66, v96
	v_pk_mul_f32 v[28:29], v[32:33], v[28:29]
	v_lshlrev_b32_e32 v32, 16, v35
	v_lshlrev_b32_e32 v33, 16, v43
	v_mov_b32_e32 v66, v74
	v_fma_f32 v74, v92, v97, 0
	v_pk_mul_f32 v[28:29], v[28:29], v[32:33]
	v_mov_b32_e32 v58, v63
	v_add_f32_e32 v28, v74, v28
	v_add_f32_e32 v42, v28, v29
	v_and_b32_e32 v29, 0xffff0000, v47
	v_and_b32_e32 v28, 0xffff0000, v31
	v_pk_mul_f32 v[28:29], v[58:59], v[28:29]
	v_and_b32_e32 v31, 0xffff0000, v43
	v_and_b32_e32 v30, 0xffff0000, v35
	v_fma_f32 v75, v94, v99, 0
	v_pk_mul_f32 v[28:29], v[28:29], v[30:31]
	v_pk_mul_f32 v[52:53], v[76:77], v[52:53]
	v_add_f32_e32 v28, v75, v28
	v_fma_f32 v60, v86, v87, 0
	v_pk_mul_f32 v[50:51], v[52:53], v[54:55]
	v_add_f32_e32 v31, v28, v29
	v_mov_b64_e32 v[28:29], s[2:3]
	v_pk_mul_f32 v[64:65], v[66:67], v[80:81]
	v_add_f32_e32 v41, v60, v50
	v_mad_i64_i32 v[28:29], s[2:3], v124, s51, v[28:29]
	v_fma_f32 v70, v70, v89, 0
	v_pk_mul_f32 v[52:53], v[64:65], v[82:83]
	v_add_f32_e32 v40, v40, v49
	v_add_f32_e32 v41, v41, v51
	v_lshl_add_u64 v[32:33], v[28:29], 0, v[192:193]
	v_lshlrev_b32_e32 v28, 16, v36
	v_and_b32_e32 v29, 0xffff0000, v36
	v_add_f32_e32 v44, v70, v52
	v_mul_f32_e32 v28, v40, v28
	v_mul_f32_e32 v29, v41, v29
	v_add_f32_e32 v44, v44, v53
	v_cvt_pk_bf16_f32 v28, v28, v29
	v_lshlrev_b32_e32 v29, 16, v37
	v_and_b32_e32 v30, 0xffff0000, v37
	v_mul_f32_e32 v29, v44, v29
	v_mul_f32_e32 v30, v45, v30
	v_cvt_pk_bf16_f32 v29, v29, v30
	v_lshlrev_b32_e32 v30, 16, v38
	v_and_b32_e32 v35, 0xffff0000, v38
	v_mul_f32_e32 v30, v48, v30
	v_mul_f32_e32 v34, v34, v35
	v_and_b32_e32 v35, 0xffff0000, v39
	v_add_co_u32_e32 v32, vcc, 0x1000, v32
	v_cvt_pk_bf16_f32 v30, v30, v34
	v_lshlrev_b32_e32 v34, 16, v39
	v_mul_f32_e32 v31, v31, v35
	v_addc_co_u32_e32 v33, vcc, 0, v33, vcc
	v_mul_f32_e32 v34, v42, v34
	v_cvt_pk_bf16_f32 v31, v34, v31
	global_store_dwordx4 v[32:33], v[28:31], off offset:1536
	s_or_b64 exec, exec, s[4:5]
	s_and_saveexec_b64 s[4:5], s[0:1]
	s_cbranch_execz .LBB0_154
; __device__ __forceinline__ unsigned cvt_pk_bf16(float lo, float hi) { unsigned r; asm volatile("v_cvt_pk_bf16_f32 %0, %1, %2" : "=v"(r) : "v"(lo), "v"(hi)); return r; }
; #define GAS __attribute__((address_space(1)))
; DI float bf_lo(unsigned w) { return __uint_as_float(w << 16); }
; DI float bf_hi(unsigned w) { return __uint_as_float(w & 0xffff0000u); }
; DI void phase_mix(const Ctx& C, bf16_t* Z, const float* lse_, int L, bool dry) {
;     ...
;         for (int k = 0; k < 4; ++k) {
;             const int idx = base + k * ngt; const int lrow = idx >> 6, c0 = (idx & 63) * 8;
;             if (idx < MTOK * 64) {
;                 float accv[8];
; #pragma unroll
;                 for (int e = 0; e < 8; ++e) accv[e] = 0.f;
; #pragma unroll
;                 for (int jj = 0; jj < 3; ++jj) {
;                     const f32x4 w0 = *(const GAS f32x4*)(cw + jj * 512 + c0), w1 = *(const GAS f32x4*)(cw + jj * 512 + c0 + 4);
;                     const u32x4 x_ = xv[k][jj], c_ = cv[k][jj];
;                     accv[0] += w0.x * bf_lo(x_.x) * bf_lo(c_.x); accv[1] += w0.y * bf_hi(x_.x) * bf_hi(c_.x);
;                     accv[2] += w0.z * bf_lo(x_.y) * bf_lo(c_.y); accv[3] += w0.w * bf_hi(x_.y) * bf_hi(c_.y);
;                     accv[4] += w1.x * bf_lo(x_.z) * bf_lo(c_.z); accv[5] += w1.y * bf_hi(x_.z) * bf_hi(c_.z);
;                     accv[6] += w1.z * bf_lo(x_.w) * bf_lo(c_.w); accv[7] += w1.w * bf_hi(x_.w) * bf_hi(c_.w);
;                 }
;                 bf16_t* bp = Z + (size_t)lrow * ZW + CB + c0;
;                 u32x4 w;
;                 w.x = cvt_pk_bf16(bf_lo(bv[k].x) * accv[0], bf_hi(bv[k].x) * accv[1]); w.y = cvt_pk_bf16(bf_lo(bv[k].y) * accv[2], bf_hi(bv[k].y) * accv[3]);
;                 w.z = cvt_pk_bf16(bf_lo(bv[k].z) * accv[4], bf_hi(bv[k].z) * accv[5]); w.w = cvt_pk_bf16(bf_lo(bv[k].w) * accv[6], bf_hi(bv[k].w) * accv[7]);
;                 *(GAS u32x4*)(dry ? dummy : bp) = w;
.LBB0_188:
	v_mov_b32_e32 v40, v152
	v_mov_b32_e32 v41, v153
	v_mov_b32_e32 v42, v154
	v_mov_b32_e32 v43, v155
	v_mov_b32_e32 v36, v156
	v_mov_b32_e32 v37, v157
	v_mov_b32_e32 v38, v158
	v_mov_b32_e32 v39, v159
	v_mov_b32_e32 v44, v160
	v_mov_b32_e32 v45, v161
	v_mov_b32_e32 v46, v162
	v_mov_b32_e32 v47, v163
	v_mov_b32_e32 v48, v168
	v_mov_b32_e32 v49, v169
	v_mov_b32_e32 v50, v170
	v_mov_b32_e32 v51, v171
	v_mov_b32_e32 v32, v164
	v_mov_b32_e32 v33, v165
	v_mov_b32_e32 v34, v166
	v_mov_b32_e32 v35, v167
	v_mov_b32_e32 v28, v172
	v_mov_b32_e32 v29, v173
	v_mov_b32_e32 v30, v174
	v_mov_b32_e32 v31, v175
	v_and_b32_e32 v62, 0xffff0000, v21
	v_and_b32_e32 v66, 0xffff0000, v22
	v_and_b32_e32 v70, 0xffff0000, v23
	v_lshlrev_b32_e32 v56, 16, v20
	v_and_b32_e32 v58, 0xffff0000, v20
	v_lshlrev_b32_e32 v60, 16, v21
	v_lshlrev_b32_e32 v61, 16, v25
	v_and_b32_e32 v63, 0xffff0000, v25
	v_lshlrev_b32_e32 v64, 16, v22
	v_lshlrev_b32_e32 v21, 16, v16
	v_and_b32_e32 v25, 0xffff0000, v16
	v_lshlrev_b32_e32 v53, 16, v17
	v_and_b32_e32 v17, 0xffff0000, v17
	v_and_b32_e32 v16, 0xffff0000, v1
	v_lshlrev_b32_e32 v57, 16, v24
	v_and_b32_e32 v59, 0xffff0000, v24
	v_lshlrev_b32_e32 v65, 16, v26
	v_and_b32_e32 v67, 0xffff0000, v26
	v_lshlrev_b32_e32 v20, 16, v0
	v_lshlrev_b32_e32 v22, 16, v4
	v_and_b32_e32 v24, 0xffff0000, v0
	v_and_b32_e32 v26, 0xffff0000, v4
	v_lshlrev_b32_e32 v52, 16, v1
	v_lshlrev_b32_e32 v54, 16, v5
	v_and_b32_e32 v1, 0xffff0000, v13
	v_and_b32_e32 v0, 0xffff0000, v5
	v_lshlrev_b32_e32 v5, 16, v18
	v_lshlrev_b32_e32 v4, 16, v2
	v_lshlrev_b32_e32 v68, 16, v23
	v_lshlrev_b32_e32 v69, 16, v27
	v_and_b32_e32 v71, 0xffff0000, v27
	v_lshlrev_b32_e32 v23, 16, v12
	v_and_b32_e32 v27, 0xffff0000, v12
	v_lshlrev_b32_e32 v55, 16, v13
	v_lshlrev_b32_e32 v13, 16, v14
	v_lshlrev_b32_e32 v12, 16, v6
	v_readlane_b32 s0, v253, 51
	v_readlane_b32 s1, v253, 52
	v_mul_f32_e32 v43, v43, v62
	v_mul_f32_e32 v62, v37, v66
	v_mul_f32_e32 v66, v39, v70
	v_mov_b32_e32 v39, v50
	v_mov_b32_e32 v50, v47
	v_mul_f32_e32 v56, v40, v56
	v_mul_f32_e32 v58, v41, v58
	v_mul_f32_e32 v42, v42, v60
	v_mul_f32_e32 v60, v36, v64
	v_mov_b32_e32 v36, v44
	v_mov_b32_e32 v37, v48
	v_mov_b32_e32 v40, v32
	v_mov_b32_e32 v41, v28
	v_pk_mul_f32 v[16:17], v[50:51], v[16:17]
	v_fma_f32 v43, v43, v63, 0
	v_pk_mul_f32 v[20:21], v[36:37], v[20:21]
	v_pk_mul_f32 v[4:5], v[40:41], v[4:5]
	v_pk_mul_f32 v[0:1], v[16:17], v[0:1]
	v_fma_f32 v28, v56, v57, 0
	v_fma_f32 v44, v60, v65, 0
	v_pk_mul_f32 v[20:21], v[20:21], v[22:23]
	v_pk_mul_f32 v[4:5], v[4:5], v[12:13]
	v_add_f32_e32 v0, v43, v0
	v_add_f32_e32 v12, v28, v20
	v_add_f32_e32 v4, v44, v4
	v_add_f32_e32 v17, v0, v1
	v_and_b32_e32 v1, 0xffff0000, v18
	v_and_b32_e32 v0, 0xffff0000, v2
	v_mov_b32_e32 v28, v33
	v_add_f32_e32 v20, v4, v5
	v_pk_mul_f32 v[0:1], v[28:29], v[0:1]
	v_and_b32_e32 v5, 0xffff0000, v14
	v_and_b32_e32 v4, 0xffff0000, v6
	v_mov_b32_e32 v48, v45
	v_fma_f32 v45, v62, v67, 0
	v_pk_mul_f32 v[0:1], v[0:1], v[4:5]
	v_mov_b32_e32 v4, v34
	v_add_f32_e32 v0, v45, v0
	v_add_f32_e32 v6, v0, v1
	v_lshlrev_b32_e32 v0, 16, v3
	v_lshlrev_b32_e32 v1, 16, v19
	v_mov_b32_e32 v5, v30
	v_mul_f32_e32 v64, v38, v68
	v_pk_mul_f32 v[0:1], v[4:5], v[0:1]
	v_lshlrev_b32_e32 v4, 16, v7
	v_lshlrev_b32_e32 v5, 16, v15
	v_mov_b32_e32 v38, v46
	v_fma_f32 v46, v64, v69, 0
	v_pk_mul_f32 v[0:1], v[0:1], v[4:5]
	v_mov_b32_e32 v30, v35
	v_add_f32_e32 v0, v46, v0
	v_add_f32_e32 v14, v0, v1
	v_and_b32_e32 v1, 0xffff0000, v19
	v_and_b32_e32 v0, 0xffff0000, v3
	v_pk_mul_f32 v[0:1], v[30:31], v[0:1]
	v_and_b32_e32 v3, 0xffff0000, v15
	v_and_b32_e32 v2, 0xffff0000, v7
	v_fma_f32 v47, v66, v71, 0
	v_pk_mul_f32 v[0:1], v[0:1], v[2:3]
	v_pk_mul_f32 v[24:25], v[48:49], v[24:25]
	v_add_f32_e32 v0, v47, v0
	v_fma_f32 v32, v58, v59, 0
	v_pk_mul_f32 v[22:23], v[24:25], v[26:27]
	v_add_f32_e32 v3, v0, v1
	v_mov_b64_e32 v[0:1], s[0:1]
	v_pk_mul_f32 v[36:37], v[38:39], v[52:53]
	v_add_f32_e32 v13, v32, v22
	v_mad_i64_i32 v[0:1], s[0:1], v123, s51, v[0:1]
	v_fma_f32 v42, v42, v61, 0
	v_pk_mul_f32 v[24:25], v[36:37], v[54:55]
	v_add_f32_e32 v12, v12, v21
	v_add_f32_e32 v13, v13, v23
	v_lshl_add_u64 v[4:5], v[0:1], 0, v[192:193]
	v_lshlrev_b32_e32 v0, 16, v8
	v_and_b32_e32 v1, 0xffff0000, v8
	v_add_f32_e32 v16, v42, v24
	v_mul_f32_e32 v0, v12, v0
	v_mul_f32_e32 v1, v13, v1
	v_add_f32_e32 v16, v16, v25
	v_cvt_pk_bf16_f32 v0, v0, v1
	v_lshlrev_b32_e32 v1, 16, v9
	v_and_b32_e32 v2, 0xffff0000, v9
	v_mul_f32_e32 v1, v16, v1
	v_mul_f32_e32 v2, v17, v2
	v_cvt_pk_bf16_f32 v1, v1, v2
	v_lshlrev_b32_e32 v2, 16, v10
	v_and_b32_e32 v7, 0xffff0000, v10
	v_mul_f32_e32 v2, v20, v2
	v_mul_f32_e32 v6, v6, v7
	v_and_b32_e32 v7, 0xffff0000, v11
	v_add_co_u32_e32 v4, vcc, 0x1000, v4
	v_cvt_pk_bf16_f32 v2, v2, v6
	v_lshlrev_b32_e32 v6, 16, v11
	v_mul_f32_e32 v3, v3, v7
	v_addc_co_u32_e32 v5, vcc, 0, v5, vcc
	v_mul_f32_e32 v6, v14, v6
	v_cvt_pk_bf16_f32 v3, v6, v3
	global_store_dwordx4 v[4:5], v[0:3], off offset:1536
	s_branch .LBB0_154
